# v41 + grid-barrier and panel-sync spin loops poll without the s_sleep 1 back-off
# speedup vs baseline: 1.0051x; 1.0051x over previous
; __global__ void __launch_bounds__(512, 2) mk_fwd(Args a) {
;     ...
;     grid.sync();
.LBB0_109:
	global_load_dword v3, v0, s[2:3] offset:32 sc1
	s_waitcnt vmcnt(0)
	v_and_b32_e32 v3, 0xffff0000, v3
	v_cmp_ne_u32_e32 vcc, v3, v2
	s_or_b64 s[4:5], vcc, s[4:5]
	s_andn2_b64 exec, exec, s[4:5]
	s_cbranch_execnz .LBB0_109

; __device__ __forceinline__ unsigned xb_ld(unsigned* p)              { return __hip_atomic_load(p, __ATOMIC_RELAXED, __HIP_MEMORY_SCOPE_AGENT); }
; __device__ __forceinline__ void xcd_barrier_complete(unsigned* bar, unsigned x, unsigned& nloc, unsigned& nx) {
;     ...
;     for (;;) {
;         sum = 0u; cnt = 0u; mine = 0u;
; #pragma unroll
;         for (unsigned j = 0; j < 16; ++j) { const unsigned c = xb_ld(&bar[XB_XCNT(j)]); sum += c; cnt += (c > 0u) ? 1u : 0u; mine = (j == x) ? c : mine; }
;         if (sum == G) break;
;         __builtin_amdgcn_s_sleep(1);
;         if ((++sp & 255u) == 0u) { if (xb_ld(&bar[XB_TMO])) break; if (sp > XB_SPIN_CAP) { atomicAdd(&bar[XB_TMO], 1u); break; } }
;     }
.LBB0_160:
	global_load_dword v15, v217, s[66:67] offset:1024 sc1
	s_waitcnt lgkmcnt(0)
	global_load_dword v0, v217, s[66:67] offset:1280 sc1
	global_load_dword v1, v217, s[66:67] offset:1536 sc1
	global_load_dword v2, v217, s[66:67] offset:1792 sc1
	global_load_dword v3, v217, s[66:67] offset:2048 sc1
	global_load_dword v4, v217, s[66:67] offset:2304 sc1
	global_load_dword v5, v217, s[66:67] offset:2560 sc1
	global_load_dword v6, v217, s[66:67] offset:2816 sc1
	global_load_dword v7, v217, s[66:67] offset:3072 sc1
	global_load_dword v8, v217, s[66:67] offset:3328 sc1
	global_load_dword v9, v217, s[66:67] offset:3584 sc1
	global_load_dword v10, v217, s[66:67] offset:3840 sc1
	global_load_dword v11, v217, s[86:87] sc1
	global_load_dword v12, v217, s[46:47] sc1
	global_load_dword v13, v217, s[34:35] sc1
	global_load_dword v14, v217, s[36:37] sc1
	s_mov_b64 s[10:11], -1
	s_mov_b64 s[16:17], -1
	s_waitcnt vmcnt(14)
	v_add_u32_e32 v16, v0, v15
	s_waitcnt vmcnt(13)
	v_add_u32_e32 v16, v16, v1
	s_waitcnt vmcnt(12)
	v_add_u32_e32 v16, v16, v2
	s_waitcnt vmcnt(11)
	v_add_u32_e32 v16, v16, v3
	s_waitcnt vmcnt(10)
	v_add_u32_e32 v16, v16, v4
	s_waitcnt vmcnt(9)
	v_add_u32_e32 v16, v16, v5
	s_waitcnt vmcnt(8)
	v_add_u32_e32 v16, v16, v6
	s_waitcnt vmcnt(7)
	v_add_u32_e32 v16, v16, v7
	s_waitcnt vmcnt(6)
	v_add_u32_e32 v16, v16, v8
	s_waitcnt vmcnt(5)
	v_add_u32_e32 v16, v16, v9
	s_waitcnt vmcnt(4)
	v_add_u32_e32 v16, v16, v10
	s_waitcnt vmcnt(3)
	v_add_u32_e32 v16, v16, v11
	s_waitcnt vmcnt(2)
	v_add_u32_e32 v16, v16, v12
	s_waitcnt vmcnt(1)
	v_add_u32_e32 v16, v16, v13
	s_waitcnt vmcnt(0)
	v_add_u32_e32 v16, v16, v14
	v_cmp_eq_u32_e32 vcc, s79, v16
	s_cbranch_vccnz .LBB0_159
	s_and_b32 s10, s2, 0xff
	s_cmp_eq_u32 s10, 0
	s_mov_b64 s[10:11], -1
	s_mov_b64 s[20:21], -1
	s_cbranch_scc1 .LBB0_164
	s_and_b64 vcc, exec, s[20:21]
	s_cbranch_vccz .LBB0_159

.LBB0_178:
	s_and_b32 s13, s2, 0xff
	s_mov_b64 s[40:41], -1
	s_cmp_lg_u32 s13, 0
	s_mov_b64 s[44:45], -1
	s_cbranch_scc0 .LBB0_181
	s_and_b64 vcc, exec, s[44:45]
	s_cbranch_vccz .LBB0_177

; __device__ __forceinline__ unsigned xb_ld(unsigned* p)              { return __hip_atomic_load(p, __ATOMIC_RELAXED, __HIP_MEMORY_SCOPE_AGENT); }
; __device__ __forceinline__ void xcd_barrier_complete(unsigned* bar, unsigned x, unsigned& nloc, unsigned& nx) {
;     ...
;     for (;;) {
;         sum = 0u; cnt = 0u; mine = 0u;
; #pragma unroll
;         for (unsigned j = 0; j < 16; ++j) { const unsigned c = xb_ld(&bar[XB_XCNT(j)]); sum += c; cnt += (c > 0u) ? 1u : 0u; mine = (j == x) ? c : mine; }
;         if (sum == G) break;
;         __builtin_amdgcn_s_sleep(1);
;         if ((++sp & 255u) == 0u) { if (xb_ld(&bar[XB_TMO])) break; if (sp > XB_SPIN_CAP) { atomicAdd(&bar[XB_TMO], 1u); break; } }
;     }
.LBB0_221:
	global_load_dword v15, v217, s[66:67] offset:1024 sc1
	s_waitcnt lgkmcnt(0)
	global_load_dword v0, v217, s[66:67] offset:1280 sc1
	global_load_dword v1, v217, s[66:67] offset:1536 sc1
	global_load_dword v2, v217, s[66:67] offset:1792 sc1
	global_load_dword v3, v217, s[66:67] offset:2048 sc1
	global_load_dword v4, v217, s[66:67] offset:2304 sc1
	global_load_dword v5, v217, s[66:67] offset:2560 sc1
	global_load_dword v6, v217, s[66:67] offset:2816 sc1
	global_load_dword v7, v217, s[66:67] offset:3072 sc1
	global_load_dword v8, v217, s[66:67] offset:3328 sc1
	global_load_dword v9, v217, s[66:67] offset:3584 sc1
	global_load_dword v10, v217, s[66:67] offset:3840 sc1
	global_load_dword v11, v217, s[86:87] sc1
	global_load_dword v12, v217, s[46:47] sc1
	global_load_dword v13, v217, s[34:35] sc1
	global_load_dword v14, v217, s[36:37] sc1
	s_mov_b64 s[4:5], -1
	s_mov_b64 s[8:9], -1
	s_waitcnt vmcnt(14)
	v_add_u32_e32 v16, v0, v15
	s_waitcnt vmcnt(13)
	v_add_u32_e32 v16, v16, v1
	s_waitcnt vmcnt(12)
	v_add_u32_e32 v16, v16, v2
	s_waitcnt vmcnt(11)
	v_add_u32_e32 v16, v16, v3
	s_waitcnt vmcnt(10)
	v_add_u32_e32 v16, v16, v4
	s_waitcnt vmcnt(9)
	v_add_u32_e32 v16, v16, v5
	s_waitcnt vmcnt(8)
	v_add_u32_e32 v16, v16, v6
	s_waitcnt vmcnt(7)
	v_add_u32_e32 v16, v16, v7
	s_waitcnt vmcnt(6)
	v_add_u32_e32 v16, v16, v8
	s_waitcnt vmcnt(5)
	v_add_u32_e32 v16, v16, v9
	s_waitcnt vmcnt(4)
	v_add_u32_e32 v16, v16, v10
	s_waitcnt vmcnt(3)
	v_add_u32_e32 v16, v16, v11
	s_waitcnt vmcnt(2)
	v_add_u32_e32 v16, v16, v12
	s_waitcnt vmcnt(1)
	v_add_u32_e32 v16, v16, v13
	s_waitcnt vmcnt(0)
	v_add_u32_e32 v16, v16, v14
	v_cmp_eq_u32_e32 vcc, s79, v16
	s_cbranch_vccnz .LBB0_220
	s_and_b32 s4, s2, 0xff
	s_cmp_eq_u32 s4, 0
	s_mov_b64 s[4:5], -1
	s_mov_b64 s[10:11], -1
	s_cbranch_scc1 .LBB0_225
	s_and_b64 vcc, exec, s[10:11]
	s_cbranch_vccz .LBB0_220

.LBB0_239:
	s_and_b32 s13, s2, 0xff
	s_mov_b64 s[20:21], -1
	s_cmp_lg_u32 s13, 0
	s_mov_b64 s[40:41], -1
	s_cbranch_scc0 .LBB0_242
	s_and_b64 vcc, exec, s[40:41]
	s_cbranch_vccz .LBB0_238

.LBB0_701:
	s_and_b32 s13, s2, 0xff
	s_mov_b64 s[20:21], -1
	s_cmp_lg_u32 s13, 0
	s_mov_b64 s[42:43], -1
	s_cbranch_scc0 .LBB0_704
	s_and_b64 vcc, exec, s[42:43]
	s_cbranch_vccz .LBB0_700
